# q up-projection GEMM epilogue rewritten like the w_in one: masks/base once per tile, permlane16_swap pairs -> two dwordx4 stores per row group instead of four exec-masked dwordx2 branches
# speedup vs baseline: 1.0118x; 1.0037x over previous
.LBB0_522:
	s_add_i32 s4, s4, 2
	s_cmp_lg_u32 s4, 4
	s_cbranch_scc1 .LBB0_501
	s_waitcnt vmcnt(7)
	v_mov_b32_e32 v131, v0
	s_lshl_b32 s2, s27, 8
	v_lshrrev_b32_e32 v132, 2, v131
	v_and_b32_e32 v130, 0xc0, v131
	v_and_b32_e32 v132, 12, v132
	v_or3_b32 v130, v130, s2, v132
	v_ashrrev_i32_e32 v132, 1, v131
	v_and_b32_e32 v132, 0xffffff80, v132
	v_lshl_add_u32 v132, s34, 8, v132
	v_and_or_b32 v132, v131, 15, v132
	v_cmp_gt_i32_e32 vcc, s40, v130
	v_ashrrev_i32_e32 v131, 31, v130
	v_cvt_pk_bf16_f32 v126, v126, v127
	v_cvt_pk_bf16_f32 v127, v128, v129
	v_cvt_pk_bf16_f32 v128, v122, v123
	v_cvt_pk_bf16_f32 v129, v124, v125
	v_cvt_pk_bf16_f32 v118, v118, v119
	v_cvt_pk_bf16_f32 v119, v120, v121
	v_cvt_pk_bf16_f32 v120, v114, v115
	v_cvt_pk_bf16_f32 v121, v116, v117
	s_mov_b32 s2, 0xffff
	s_mov_b32 s3, 0xffff
	v_add_u32_e32 v114, 16, v130
	v_cmp_gt_i32_e64 s[4:5], s40, v114
	s_and_b64 vcc, vcc, s[2:3]
	s_andn2_b64 s[4:5], s[4:5], s[2:3]
	s_or_b64 s[4:5], s[4:5], vcc
	v_add_u32_e32 v114, 32, v130
	v_cmp_gt_i32_e32 vcc, s40, v114
	v_add_u32_e32 v114, 48, v130
	v_cmp_gt_i32_e64 s[6:7], s40, v114
	s_and_b64 vcc, vcc, s[2:3]
	s_andn2_b64 s[6:7], s[6:7], s[2:3]
	s_or_b64 s[6:7], s[6:7], vcc
	s_lshl_b32 s2, s41, 4
	s_mov_b32 s3, 0
	v_mov_b64_e32 v[122:123], s[20:21]
	v_mad_i64_i32 v[122:123], vcc, v132, s41, v[122:123]
	v_lshl_add_u64 v[122:123], v[130:131], 1, v[122:123]
	v_bfe_u32 v114, v0, 4, 1
	v_mul_u32_u24_e32 v114, 24, v114
	v_mov_b32_e32 v115, 0
	v_lshl_add_u64 v[124:125], v[122:123], 0, v[114:115]
	v_permlane16_swap_b32_e32 v126, v128
	v_permlane16_swap_b32_e32 v127, v129
	v_permlane16_swap_b32_e32 v118, v120
	v_permlane16_swap_b32_e32 v119, v121
	s_mov_b64 exec, s[4:5]
	global_store_dwordx4 v[124:125], v[126:129], off
	s_mov_b64 exec, s[6:7]
	global_store_dwordx4 v[124:125], v[118:121], off offset:64
	s_mov_b64 exec, -1
	v_lshl_add_u64 v[124:125], v[124:125], 0, s[2:3]
	v_cvt_pk_bf16_f32 v110, v110, v111
	v_cvt_pk_bf16_f32 v111, v112, v113
	v_cvt_pk_bf16_f32 v112, v106, v107
	v_cvt_pk_bf16_f32 v113, v108, v109
	v_cvt_pk_bf16_f32 v102, v102, v103
	v_cvt_pk_bf16_f32 v103, v104, v105
	v_cvt_pk_bf16_f32 v104, v98, v99
	v_cvt_pk_bf16_f32 v105, v100, v101
	s_nop 1
	v_permlane16_swap_b32_e32 v110, v112
	v_permlane16_swap_b32_e32 v111, v113
	v_permlane16_swap_b32_e32 v102, v104
	v_permlane16_swap_b32_e32 v103, v105
	s_mov_b64 exec, s[4:5]
	global_store_dwordx4 v[124:125], v[110:113], off
	s_mov_b64 exec, s[6:7]
	global_store_dwordx4 v[124:125], v[102:105], off offset:64
	s_mov_b64 exec, -1
	v_lshl_add_u64 v[124:125], v[124:125], 0, s[2:3]
	v_cvt_pk_bf16_f32 v94, v94, v95
	v_cvt_pk_bf16_f32 v95, v96, v97
	v_cvt_pk_bf16_f32 v96, v90, v91
	v_cvt_pk_bf16_f32 v97, v92, v93
	v_cvt_pk_bf16_f32 v86, v86, v87
	v_cvt_pk_bf16_f32 v87, v88, v89
	v_cvt_pk_bf16_f32 v88, v82, v83
	v_cvt_pk_bf16_f32 v89, v84, v85
	s_nop 1
	v_permlane16_swap_b32_e32 v94, v96
	v_permlane16_swap_b32_e32 v95, v97
	v_permlane16_swap_b32_e32 v86, v88
	v_permlane16_swap_b32_e32 v87, v89
	s_mov_b64 exec, s[4:5]
	global_store_dwordx4 v[124:125], v[94:97], off
	s_mov_b64 exec, s[6:7]
	global_store_dwordx4 v[124:125], v[86:89], off offset:64
	s_mov_b64 exec, -1
	v_lshl_add_u64 v[124:125], v[124:125], 0, s[2:3]
	v_cvt_pk_bf16_f32 v78, v78, v79
	v_cvt_pk_bf16_f32 v79, v80, v81
	v_cvt_pk_bf16_f32 v80, v74, v75
	v_cvt_pk_bf16_f32 v81, v76, v77
	v_cvt_pk_bf16_f32 v70, v70, v71
	v_cvt_pk_bf16_f32 v71, v72, v73
	v_cvt_pk_bf16_f32 v72, v42, v43
	v_cvt_pk_bf16_f32 v73, v44, v45
	s_nop 1
	v_permlane16_swap_b32_e32 v78, v80
	v_permlane16_swap_b32_e32 v79, v81
	v_permlane16_swap_b32_e32 v70, v72
	v_permlane16_swap_b32_e32 v71, v73
	s_mov_b64 exec, s[4:5]
	global_store_dwordx4 v[124:125], v[78:81], off
	s_mov_b64 exec, s[6:7]
	global_store_dwordx4 v[124:125], v[70:73], off offset:64
	s_mov_b64 exec, -1
	v_lshl_add_u64 v[124:125], v[124:125], 0, s[2:3]
	v_cvt_pk_bf16_f32 v66, v66, v67
	v_cvt_pk_bf16_f32 v67, v68, v69
	v_cvt_pk_bf16_f32 v68, v62, v63
	v_cvt_pk_bf16_f32 v69, v64, v65
	v_cvt_pk_bf16_f32 v58, v58, v59
	v_cvt_pk_bf16_f32 v59, v60, v61
	v_cvt_pk_bf16_f32 v60, v54, v55
	v_cvt_pk_bf16_f32 v61, v56, v57
	s_nop 1
	v_permlane16_swap_b32_e32 v66, v68
	v_permlane16_swap_b32_e32 v67, v69
	v_permlane16_swap_b32_e32 v58, v60
	v_permlane16_swap_b32_e32 v59, v61
	s_mov_b64 exec, s[4:5]
	global_store_dwordx4 v[124:125], v[66:69], off
	s_mov_b64 exec, s[6:7]
	global_store_dwordx4 v[124:125], v[58:61], off offset:64
	s_mov_b64 exec, -1
	v_lshl_add_u64 v[124:125], v[124:125], 0, s[2:3]
	v_cvt_pk_bf16_f32 v50, v50, v51
	v_cvt_pk_bf16_f32 v51, v52, v53
	v_cvt_pk_bf16_f32 v52, v46, v47
	v_cvt_pk_bf16_f32 v53, v48, v49
	v_cvt_pk_bf16_f32 v38, v38, v39
	v_cvt_pk_bf16_f32 v39, v40, v41
	v_cvt_pk_bf16_f32 v40, v34, v35
	v_cvt_pk_bf16_f32 v41, v36, v37
	s_nop 1
	v_permlane16_swap_b32_e32 v50, v52
	v_permlane16_swap_b32_e32 v51, v53
	v_permlane16_swap_b32_e32 v38, v40
	v_permlane16_swap_b32_e32 v39, v41
	s_mov_b64 exec, s[4:5]
	global_store_dwordx4 v[124:125], v[50:53], off
	s_mov_b64 exec, s[6:7]
	global_store_dwordx4 v[124:125], v[38:41], off offset:64
	s_mov_b64 exec, -1
	v_lshl_add_u64 v[124:125], v[124:125], 0, s[2:3]
	v_cvt_pk_bf16_f32 v30, v30, v31
	v_cvt_pk_bf16_f32 v31, v32, v33
	v_cvt_pk_bf16_f32 v32, v26, v27
	v_cvt_pk_bf16_f32 v33, v28, v29
	v_cvt_pk_bf16_f32 v22, v22, v23
	v_cvt_pk_bf16_f32 v23, v24, v25
	v_cvt_pk_bf16_f32 v24, v18, v19
	v_cvt_pk_bf16_f32 v25, v20, v21
	s_nop 1
	v_permlane16_swap_b32_e32 v30, v32
	v_permlane16_swap_b32_e32 v31, v33
	v_permlane16_swap_b32_e32 v22, v24
	v_permlane16_swap_b32_e32 v23, v25
	s_mov_b64 exec, s[4:5]
	global_store_dwordx4 v[124:125], v[30:33], off
	s_mov_b64 exec, s[6:7]
	global_store_dwordx4 v[124:125], v[22:25], off offset:64
	s_mov_b64 exec, -1
	v_lshl_add_u64 v[124:125], v[124:125], 0, s[2:3]
	v_cvt_pk_bf16_f32 v14, v14, v15
	v_cvt_pk_bf16_f32 v15, v16, v17
	v_cvt_pk_bf16_f32 v16, v10, v11
	v_cvt_pk_bf16_f32 v17, v12, v13
	v_cvt_pk_bf16_f32 v6, v6, v7
	v_cvt_pk_bf16_f32 v7, v8, v9
	v_cvt_pk_bf16_f32 v8, v2, v3
	v_cvt_pk_bf16_f32 v9, v4, v5
	s_nop 1
	v_permlane16_swap_b32_e32 v14, v16
	v_permlane16_swap_b32_e32 v15, v17
	v_permlane16_swap_b32_e32 v6, v8
	v_permlane16_swap_b32_e32 v7, v9
	s_mov_b64 exec, s[4:5]
	global_store_dwordx4 v[124:125], v[14:17], off
	s_mov_b64 exec, s[6:7]
	global_store_dwordx4 v[124:125], v[6:9], off offset:64
	s_mov_b64 exec, -1
	s_mov_b64 s[2:3], exec
	s_branch .LBB0_559
.LBB0_525:
.LBB0_527:
.LBB0_529:
.LBB0_531:
.LBB0_532:
.LBB0_533:
.LBB0_534:
.LBB0_535:
.LBB0_536:
.LBB0_537:
.LBB0_538:
.LBB0_539:
.LBB0_540:
.LBB0_541:
.LBB0_542:
.LBB0_543:
.LBB0_544:
.LBB0_545:
.LBB0_546:
.LBB0_547:
.LBB0_548:
.LBB0_549:
.LBB0_550:
.LBB0_551:
.LBB0_552:
.LBB0_553:
.LBB0_554:
.LBB0_555:
.LBB0_556:
.LBB0_557:
.LBB0_558:
.LBB0_559:
	s_or_b64 exec, exec, s[2:3]
	s_add_i32 s42, s42, s11
	v_mov_b32_e32 v5, 0
	s_cmp_gt_i32 s42, 23
	s_cbranch_scc1 .LBB0_500
	s_mov_b32 s4, s10
	s_cmpk_gt_i32 s42, 0xffe0
	s_mov_b64 s[2:3], -1
	s_cbranch_scc0 .LBB0_562
	s_bfe_i32 s2, s42, 0x80000
	s_mulk_i32 s2, 0x56
	s_bfe_u32 s3, s2, 0x1000f
	s_bfe_u32 s2, s2, 0x80008
	s_add_i32 s2, s2, s3
	s_sext_i32_i8 s3, s2
	s_mul_i32 s2, s2, 3
	s_sub_i32 s2, s42, s2
	s_lshl_b32 s5, s3, 3
	s_sext_i32_i8 s27, s2
	s_mov_b64 s[2:3], 0

.LBB0_564:
.LBB0_565:
.LBB0_566:
.LBB0_567:
.LBB0_568:
.LBB0_569:
.LBB0_570:
.LBB0_571:
.LBB0_572:
.LBB0_573:
.LBB0_574:
.LBB0_575:
.LBB0_576:
.LBB0_577:
.LBB0_578:
.LBB0_579:
.LBB0_580:
.LBB0_581:
.LBB0_582:
.LBB0_583:
.LBB0_584:
.LBB0_585:
.LBB0_586:
.LBB0_587:
.LBB0_588:
.LBB0_589:
.LBB0_590:
.LBB0_591:
	s_branch .LBB0_559
